# polarity check of the static priority raise: waves 0-3 (leading half) raised instead of waves 4-7 in the fp6 GEMM loops
# baseline (speedup 1.0000x reference)
.LBB0_990:
	s_ashr_i32 s45, s44, 31
	s_lshl_b64 s[4:5], s[44:45], 19
	s_add_u32 s46, s0, s4
	s_addc_u32 s47, s1, s5
	s_and_b64 s[4:5], s[6:7], exec
	s_cselect_b32 s4, s47, s55
	s_cselect_b32 s5, s46, s54
	s_ashr_i32 s39, s38, 31
	s_lshl_b64 s[48:49], s[38:39], 19
	s_add_u32 s48, s2, s48
	s_addc_u32 s49, s3, s49
	s_and_b64 s[58:59], s[6:7], exec
	s_cselect_b32 s39, s49, s57
	s_cselect_b32 s45, s48, s56
	s_add_u32 s54, s54, 0x40080
	s_addc_u32 s55, s55, 0
	s_add_u32 s84, s56, 0x100
	v_mov_b32_e32 v36, 0
	s_addc_u32 s85, s57, 0
	s_mov_b32 s86, -2
	v_mov_b32_e32 v37, v36
	v_mov_b32_e32 v38, v36
	v_mov_b32_e32 v39, v36
	v_mov_b32_e32 v40, v36
	v_mov_b32_e32 v41, v36
	v_mov_b32_e32 v42, v36
	v_mov_b32_e32 v43, v36
	v_mov_b32_e32 v48, v36
	v_mov_b32_e32 v49, v36
	v_mov_b32_e32 v50, v36
	v_mov_b32_e32 v51, v36
	v_mov_b32_e32 v60, v36
	v_mov_b32_e32 v61, v36
	v_mov_b32_e32 v62, v36
	v_mov_b32_e32 v63, v36
	v_mov_b32_e32 v64, v36
	v_mov_b32_e32 v65, v36
	v_mov_b32_e32 v66, v36
	v_mov_b32_e32 v67, v36
	v_mov_b32_e32 v72, v36
	v_mov_b32_e32 v73, v36
	v_mov_b32_e32 v74, v36
	v_mov_b32_e32 v75, v36
	v_mov_b32_e32 v84, v36
	v_mov_b32_e32 v85, v36
	v_mov_b32_e32 v86, v36
	v_mov_b32_e32 v87, v36
	v_mov_b32_e32 v88, v36
	v_mov_b32_e32 v89, v36
	v_mov_b32_e32 v90, v36
	v_mov_b32_e32 v91, v36
	v_mov_b32_e32 v44, v36
	v_mov_b32_e32 v45, v36
	v_mov_b32_e32 v46, v36
	v_mov_b32_e32 v47, v36
	v_mov_b32_e32 v52, v36
	v_mov_b32_e32 v53, v36
	v_mov_b32_e32 v54, v36
	v_mov_b32_e32 v55, v36
	v_mov_b32_e32 v56, v36
	v_mov_b32_e32 v57, v36
	v_mov_b32_e32 v58, v36
	v_mov_b32_e32 v59, v36
	v_mov_b32_e32 v68, v36
	v_mov_b32_e32 v69, v36
	v_mov_b32_e32 v70, v36
	v_mov_b32_e32 v71, v36
	v_mov_b32_e32 v76, v36
	v_mov_b32_e32 v77, v36
	v_mov_b32_e32 v78, v36
	v_mov_b32_e32 v79, v36
	v_mov_b32_e32 v80, v36
	v_mov_b32_e32 v81, v36
	v_mov_b32_e32 v82, v36
	v_mov_b32_e32 v83, v36
	v_mov_b32_e32 v92, v36
	v_mov_b32_e32 v93, v36
	v_mov_b32_e32 v94, v36
	v_mov_b32_e32 v95, v36
	v_mov_b32_e32 v96, v36
	v_mov_b32_e32 v97, v36
	v_mov_b32_e32 v98, v36
	v_mov_b32_e32 v99, v36
	v_mov_b32_e32 v30, v36
	v_mov_b32_e32 v31, v36
	v_mov_b32_e32 v32, v36
	v_mov_b32_e32 v33, v36
	v_mov_b32_e32 v26, v36
	v_mov_b32_e32 v27, v36
	v_mov_b32_e32 v28, v36
	v_mov_b32_e32 v29, v36
	v_mov_b32_e32 v22, v36
	v_mov_b32_e32 v23, v36
	v_mov_b32_e32 v24, v36
	v_mov_b32_e32 v25, v36
	v_mov_b32_e32 v18, v36
	v_mov_b32_e32 v19, v36
	v_mov_b32_e32 v20, v36
	v_mov_b32_e32 v21, v36
	v_mov_b32_e32 v14, v36
	v_mov_b32_e32 v15, v36
	v_mov_b32_e32 v16, v36
	v_mov_b32_e32 v17, v36
	v_mov_b32_e32 v10, v36
	v_mov_b32_e32 v11, v36
	v_mov_b32_e32 v12, v36
	v_mov_b32_e32 v13, v36
	v_mov_b32_e32 v6, v36
	v_mov_b32_e32 v7, v36
	v_mov_b32_e32 v8, v36
	v_mov_b32_e32 v9, v36
	v_mov_b32_e32 v2, v36
	v_mov_b32_e32 v3, v36
	v_mov_b32_e32 v4, v36
	v_mov_b32_e32 v5, v36
	v_mov_b32_e32 v100, v36
	v_mov_b32_e32 v101, v36
	v_mov_b32_e32 v102, v36
	v_mov_b32_e32 v103, v36
	v_mov_b32_e32 v104, v36
	v_mov_b32_e32 v105, v36
	v_mov_b32_e32 v106, v36
	v_mov_b32_e32 v107, v36
	v_mov_b32_e32 v108, v36
	v_mov_b32_e32 v109, v36
	v_mov_b32_e32 v110, v36
	v_mov_b32_e32 v111, v36
	v_mov_b32_e32 v112, v36
	v_mov_b32_e32 v113, v36
	v_mov_b32_e32 v114, v36
	v_mov_b32_e32 v115, v36
	v_mov_b32_e32 v116, v36
	v_mov_b32_e32 v117, v36
	v_mov_b32_e32 v118, v36
	v_mov_b32_e32 v119, v36
	v_mov_b32_e32 v120, v36
	v_mov_b32_e32 v121, v36
	v_mov_b32_e32 v122, v36
	v_mov_b32_e32 v123, v36
	v_mov_b32_e32 v124, v36
	v_mov_b32_e32 v125, v36
	v_mov_b32_e32 v126, v36
	v_mov_b32_e32 v127, v36
	v_mov_b32_e32 v128, v36
	v_mov_b32_e32 v129, v36
	v_mov_b32_e32 v130, v36
	v_mov_b32_e32 v131, v36
	v_readfirstlane_b32 s100, v0
	s_bitcmp0_b32 s100, 8
	s_cbranch_scc0 .Lfp6_prio_skip0
	s_setprio 1

.LBB0_1073:
	s_add_u32 s48, s48, 0xb0080
	s_addc_u32 s49, s49, 0
	s_add_u32 s4, s52, 0x100
	v_mov_b32_e32 v2, 0
	s_addc_u32 s5, s53, 0
	s_mov_b32 s63, -2
	v_mov_b32_e32 v3, v2
	v_mov_b32_e32 v4, v2
	v_mov_b32_e32 v5, v2
	v_mov_b32_e32 v6, v2
	v_mov_b32_e32 v7, v2
	v_mov_b32_e32 v8, v2
	v_mov_b32_e32 v9, v2
	v_mov_b32_e32 v18, v2
	v_mov_b32_e32 v19, v2
	v_mov_b32_e32 v20, v2
	v_mov_b32_e32 v21, v2
	v_mov_b32_e32 v22, v2
	v_mov_b32_e32 v23, v2
	v_mov_b32_e32 v24, v2
	v_mov_b32_e32 v25, v2
	v_mov_b32_e32 v34, v2
	v_mov_b32_e32 v35, v2
	v_mov_b32_e32 v36, v2
	v_mov_b32_e32 v37, v2
	v_mov_b32_e32 v38, v2
	v_mov_b32_e32 v39, v2
	v_mov_b32_e32 v40, v2
	v_mov_b32_e32 v41, v2
	v_mov_b32_e32 v50, v2
	v_mov_b32_e32 v51, v2
	v_mov_b32_e32 v52, v2
	v_mov_b32_e32 v53, v2
	v_mov_b32_e32 v54, v2
	v_mov_b32_e32 v55, v2
	v_mov_b32_e32 v56, v2
	v_mov_b32_e32 v57, v2
	v_mov_b32_e32 v10, v2
	v_mov_b32_e32 v11, v2
	v_mov_b32_e32 v12, v2
	v_mov_b32_e32 v13, v2
	v_mov_b32_e32 v14, v2
	v_mov_b32_e32 v15, v2
	v_mov_b32_e32 v16, v2
	v_mov_b32_e32 v17, v2
	v_mov_b32_e32 v26, v2
	v_mov_b32_e32 v27, v2
	v_mov_b32_e32 v28, v2
	v_mov_b32_e32 v29, v2
	v_mov_b32_e32 v30, v2
	v_mov_b32_e32 v31, v2
	v_mov_b32_e32 v32, v2
	v_mov_b32_e32 v33, v2
	v_mov_b32_e32 v42, v2
	v_mov_b32_e32 v43, v2
	v_mov_b32_e32 v44, v2
	v_mov_b32_e32 v45, v2
	v_mov_b32_e32 v46, v2
	v_mov_b32_e32 v47, v2
	v_mov_b32_e32 v48, v2
	v_mov_b32_e32 v49, v2
	v_mov_b32_e32 v58, v2
	v_mov_b32_e32 v59, v2
	v_mov_b32_e32 v60, v2
	v_mov_b32_e32 v61, v2
	v_mov_b32_e32 v62, v2
	v_mov_b32_e32 v63, v2
	v_mov_b32_e32 v64, v2
	v_mov_b32_e32 v65, v2
	v_mov_b32_e32 v66, v2
	v_mov_b32_e32 v67, v2
	v_mov_b32_e32 v68, v2
	v_mov_b32_e32 v69, v2
	v_mov_b32_e32 v70, v2
	v_mov_b32_e32 v71, v2
	v_mov_b32_e32 v72, v2
	v_mov_b32_e32 v73, v2
	v_mov_b32_e32 v82, v2
	v_mov_b32_e32 v83, v2
	v_mov_b32_e32 v84, v2
	v_mov_b32_e32 v85, v2
	v_mov_b32_e32 v86, v2
	v_mov_b32_e32 v87, v2
	v_mov_b32_e32 v88, v2
	v_mov_b32_e32 v89, v2
	v_mov_b32_e32 v98, v2
	v_mov_b32_e32 v99, v2
	v_mov_b32_e32 v100, v2
	v_mov_b32_e32 v101, v2
	v_mov_b32_e32 v102, v2
	v_mov_b32_e32 v103, v2
	v_mov_b32_e32 v104, v2
	v_mov_b32_e32 v105, v2
	v_mov_b32_e32 v146, v2
	v_mov_b32_e32 v147, v2
	v_mov_b32_e32 v148, v2
	v_mov_b32_e32 v149, v2
	v_mov_b32_e32 v150, v2
	v_mov_b32_e32 v151, v2
	v_mov_b32_e32 v152, v2
	v_mov_b32_e32 v153, v2
	v_mov_b32_e32 v74, v2
	v_mov_b32_e32 v75, v2
	v_mov_b32_e32 v76, v2
	v_mov_b32_e32 v77, v2
	v_mov_b32_e32 v78, v2
	v_mov_b32_e32 v79, v2
	v_mov_b32_e32 v80, v2
	v_mov_b32_e32 v81, v2
	v_mov_b32_e32 v90, v2
	v_mov_b32_e32 v91, v2
	v_mov_b32_e32 v92, v2
	v_mov_b32_e32 v93, v2
	v_mov_b32_e32 v94, v2
	v_mov_b32_e32 v95, v2
	v_mov_b32_e32 v96, v2
	v_mov_b32_e32 v97, v2
	v_mov_b32_e32 v106, v2
	v_mov_b32_e32 v107, v2
	v_mov_b32_e32 v108, v2
	v_mov_b32_e32 v109, v2
	v_mov_b32_e32 v110, v2
	v_mov_b32_e32 v111, v2
	v_mov_b32_e32 v112, v2
	v_mov_b32_e32 v113, v2
	v_mov_b32_e32 v154, v2
	v_mov_b32_e32 v155, v2
	v_mov_b32_e32 v156, v2
	v_mov_b32_e32 v157, v2
	v_mov_b32_e32 v158, v2
	v_mov_b32_e32 v159, v2
	v_mov_b32_e32 v160, v2
	v_mov_b32_e32 v161, v2
	v_readfirstlane_b32 s100, v0
	s_bitcmp0_b32 s100, 8
	s_cbranch_scc0 .Lfp6_prio_skip1
	s_setprio 1

.LBB0_2186:
	s_ashr_i32 s35, s34, 31
	s_lshl_b64 s[38:39], s[34:35], 19
	s_add_u32 s38, s1, s38
	s_addc_u32 s39, s2, s39
	s_and_b64 s[44:45], s[52:53], exec
	s_cselect_b32 s35, s39, s49
	s_cselect_b32 s47, s38, s48
	s_ashr_i32 s37, s36, 31
	s_lshl_b64 s[44:45], s[36:37], 19
	s_add_u32 s44, s3, s44
	s_addc_u32 s45, s28, s45
	s_and_b64 s[52:53], s[52:53], exec
	s_cselect_b32 s37, s45, s51
	s_cselect_b32 s65, s44, s50
	s_add_u32 s48, s48, 0x40080
	s_addc_u32 s49, s49, 0
	s_add_u32 s66, s50, 0x100
	v_mov_b32_e32 v36, 0
	s_addc_u32 s67, s51, 0
	s_mov_b32 s76, -2
	v_mov_b32_e32 v37, v36
	v_mov_b32_e32 v38, v36
	v_mov_b32_e32 v39, v36
	v_mov_b32_e32 v40, v36
	v_mov_b32_e32 v41, v36
	v_mov_b32_e32 v42, v36
	v_mov_b32_e32 v43, v36
	v_mov_b32_e32 v48, v36
	v_mov_b32_e32 v49, v36
	v_mov_b32_e32 v50, v36
	v_mov_b32_e32 v51, v36
	v_mov_b32_e32 v60, v36
	v_mov_b32_e32 v61, v36
	v_mov_b32_e32 v62, v36
	v_mov_b32_e32 v63, v36
	v_mov_b32_e32 v64, v36
	v_mov_b32_e32 v65, v36
	v_mov_b32_e32 v66, v36
	v_mov_b32_e32 v67, v36
	v_mov_b32_e32 v72, v36
	v_mov_b32_e32 v73, v36
	v_mov_b32_e32 v74, v36
	v_mov_b32_e32 v75, v36
	v_mov_b32_e32 v84, v36
	v_mov_b32_e32 v85, v36
	v_mov_b32_e32 v86, v36
	v_mov_b32_e32 v87, v36
	v_mov_b32_e32 v88, v36
	v_mov_b32_e32 v89, v36
	v_mov_b32_e32 v90, v36
	v_mov_b32_e32 v91, v36
	v_mov_b32_e32 v44, v36
	v_mov_b32_e32 v45, v36
	v_mov_b32_e32 v46, v36
	v_mov_b32_e32 v47, v36
	v_mov_b32_e32 v52, v36
	v_mov_b32_e32 v53, v36
	v_mov_b32_e32 v54, v36
	v_mov_b32_e32 v55, v36
	v_mov_b32_e32 v56, v36
	v_mov_b32_e32 v57, v36
	v_mov_b32_e32 v58, v36
	v_mov_b32_e32 v59, v36
	v_mov_b32_e32 v68, v36
	v_mov_b32_e32 v69, v36
	v_mov_b32_e32 v70, v36
	v_mov_b32_e32 v71, v36
	v_mov_b32_e32 v76, v36
	v_mov_b32_e32 v77, v36
	v_mov_b32_e32 v78, v36
	v_mov_b32_e32 v79, v36
	v_mov_b32_e32 v80, v36
	v_mov_b32_e32 v81, v36
	v_mov_b32_e32 v82, v36
	v_mov_b32_e32 v83, v36
	v_mov_b32_e32 v92, v36
	v_mov_b32_e32 v93, v36
	v_mov_b32_e32 v94, v36
	v_mov_b32_e32 v95, v36
	v_mov_b32_e32 v96, v36
	v_mov_b32_e32 v97, v36
	v_mov_b32_e32 v98, v36
	v_mov_b32_e32 v99, v36
	v_mov_b32_e32 v30, v36
	v_mov_b32_e32 v31, v36
	v_mov_b32_e32 v32, v36
	v_mov_b32_e32 v33, v36
	v_mov_b32_e32 v26, v36
	v_mov_b32_e32 v27, v36
	v_mov_b32_e32 v28, v36
	v_mov_b32_e32 v29, v36
	v_mov_b32_e32 v22, v36
	v_mov_b32_e32 v23, v36
	v_mov_b32_e32 v24, v36
	v_mov_b32_e32 v25, v36
	v_mov_b32_e32 v18, v36
	v_mov_b32_e32 v19, v36
	v_mov_b32_e32 v20, v36
	v_mov_b32_e32 v21, v36
	v_mov_b32_e32 v14, v36
	v_mov_b32_e32 v15, v36
	v_mov_b32_e32 v16, v36
	v_mov_b32_e32 v17, v36
	v_mov_b32_e32 v10, v36
	v_mov_b32_e32 v11, v36
	v_mov_b32_e32 v12, v36
	v_mov_b32_e32 v13, v36
	v_mov_b32_e32 v6, v36
	v_mov_b32_e32 v7, v36
	v_mov_b32_e32 v8, v36
	v_mov_b32_e32 v9, v36
	v_mov_b32_e32 v2, v36
	v_mov_b32_e32 v3, v36
	v_mov_b32_e32 v4, v36
	v_mov_b32_e32 v5, v36
	v_mov_b32_e32 v100, v36
	v_mov_b32_e32 v101, v36
	v_mov_b32_e32 v102, v36
	v_mov_b32_e32 v103, v36
	v_mov_b32_e32 v104, v36
	v_mov_b32_e32 v105, v36
	v_mov_b32_e32 v106, v36
	v_mov_b32_e32 v107, v36
	v_mov_b32_e32 v108, v36
	v_mov_b32_e32 v109, v36
	v_mov_b32_e32 v110, v36
	v_mov_b32_e32 v111, v36
	v_mov_b32_e32 v112, v36
	v_mov_b32_e32 v113, v36
	v_mov_b32_e32 v114, v36
	v_mov_b32_e32 v115, v36
	v_mov_b32_e32 v116, v36
	v_mov_b32_e32 v117, v36
	v_mov_b32_e32 v118, v36
	v_mov_b32_e32 v119, v36
	v_mov_b32_e32 v120, v36
	v_mov_b32_e32 v121, v36
	v_mov_b32_e32 v122, v36
	v_mov_b32_e32 v123, v36
	v_mov_b32_e32 v124, v36
	v_mov_b32_e32 v125, v36
	v_mov_b32_e32 v126, v36
	v_mov_b32_e32 v127, v36
	v_mov_b32_e32 v128, v36
	v_mov_b32_e32 v129, v36
	v_mov_b32_e32 v130, v36
	v_mov_b32_e32 v131, v36
	v_readfirstlane_b32 s100, v0
	s_bitcmp0_b32 s100, 8
	s_cbranch_scc0 .Lfp6_prio_skip2
	s_setprio 1

.LBB0_2290:
	s_add_i32 s4, s66, -2
	s_add_u32 s44, s44, 0xe0080
	s_addc_u32 s45, s45, 0
	s_add_u32 s5, s46, 0x100
	v_mov_b32_e32 v2, 0
	s_addc_u32 s67, s47, 0
	s_mov_b32 s46, 0
	v_mov_b32_e32 v3, v2
	v_mov_b32_e32 v4, v2
	v_mov_b32_e32 v5, v2
	v_mov_b32_e32 v6, v2
	v_mov_b32_e32 v7, v2
	v_mov_b32_e32 v8, v2
	v_mov_b32_e32 v9, v2
	v_mov_b32_e32 v18, v2
	v_mov_b32_e32 v19, v2
	v_mov_b32_e32 v20, v2
	v_mov_b32_e32 v21, v2
	v_mov_b32_e32 v22, v2
	v_mov_b32_e32 v23, v2
	v_mov_b32_e32 v24, v2
	v_mov_b32_e32 v25, v2
	v_mov_b32_e32 v34, v2
	v_mov_b32_e32 v35, v2
	v_mov_b32_e32 v36, v2
	v_mov_b32_e32 v37, v2
	v_mov_b32_e32 v38, v2
	v_mov_b32_e32 v39, v2
	v_mov_b32_e32 v40, v2
	v_mov_b32_e32 v41, v2
	v_mov_b32_e32 v50, v2
	v_mov_b32_e32 v51, v2
	v_mov_b32_e32 v52, v2
	v_mov_b32_e32 v53, v2
	v_mov_b32_e32 v54, v2
	v_mov_b32_e32 v55, v2
	v_mov_b32_e32 v56, v2
	v_mov_b32_e32 v57, v2
	v_mov_b32_e32 v10, v2
	v_mov_b32_e32 v11, v2
	v_mov_b32_e32 v12, v2
	v_mov_b32_e32 v13, v2
	v_mov_b32_e32 v14, v2
	v_mov_b32_e32 v15, v2
	v_mov_b32_e32 v16, v2
	v_mov_b32_e32 v17, v2
	v_mov_b32_e32 v26, v2
	v_mov_b32_e32 v27, v2
	v_mov_b32_e32 v28, v2
	v_mov_b32_e32 v29, v2
	v_mov_b32_e32 v30, v2
	v_mov_b32_e32 v31, v2
	v_mov_b32_e32 v32, v2
	v_mov_b32_e32 v33, v2
	v_mov_b32_e32 v42, v2
	v_mov_b32_e32 v43, v2
	v_mov_b32_e32 v44, v2
	v_mov_b32_e32 v45, v2
	v_mov_b32_e32 v46, v2
	v_mov_b32_e32 v47, v2
	v_mov_b32_e32 v48, v2
	v_mov_b32_e32 v49, v2
	v_mov_b32_e32 v58, v2
	v_mov_b32_e32 v59, v2
	v_mov_b32_e32 v60, v2
	v_mov_b32_e32 v61, v2
	v_mov_b32_e32 v62, v2
	v_mov_b32_e32 v63, v2
	v_mov_b32_e32 v64, v2
	v_mov_b32_e32 v65, v2
	v_mov_b32_e32 v66, v2
	v_mov_b32_e32 v67, v2
	v_mov_b32_e32 v68, v2
	v_mov_b32_e32 v69, v2
	v_mov_b32_e32 v70, v2
	v_mov_b32_e32 v71, v2
	v_mov_b32_e32 v72, v2
	v_mov_b32_e32 v73, v2
	v_mov_b32_e32 v82, v2
	v_mov_b32_e32 v83, v2
	v_mov_b32_e32 v84, v2
	v_mov_b32_e32 v85, v2
	v_mov_b32_e32 v86, v2
	v_mov_b32_e32 v87, v2
	v_mov_b32_e32 v88, v2
	v_mov_b32_e32 v89, v2
	v_mov_b32_e32 v98, v2
	v_mov_b32_e32 v99, v2
	v_mov_b32_e32 v100, v2
	v_mov_b32_e32 v101, v2
	v_mov_b32_e32 v102, v2
	v_mov_b32_e32 v103, v2
	v_mov_b32_e32 v104, v2
	v_mov_b32_e32 v105, v2
	v_mov_b32_e32 v114, v2
	v_mov_b32_e32 v115, v2
	v_mov_b32_e32 v116, v2
	v_mov_b32_e32 v117, v2
	v_mov_b32_e32 v118, v2
	v_mov_b32_e32 v119, v2
	v_mov_b32_e32 v120, v2
	v_mov_b32_e32 v121, v2
	v_mov_b32_e32 v74, v2
	v_mov_b32_e32 v75, v2
	v_mov_b32_e32 v76, v2
	v_mov_b32_e32 v77, v2
	v_mov_b32_e32 v78, v2
	v_mov_b32_e32 v79, v2
	v_mov_b32_e32 v80, v2
	v_mov_b32_e32 v81, v2
	v_mov_b32_e32 v90, v2
	v_mov_b32_e32 v91, v2
	v_mov_b32_e32 v92, v2
	v_mov_b32_e32 v93, v2
	v_mov_b32_e32 v94, v2
	v_mov_b32_e32 v95, v2
	v_mov_b32_e32 v96, v2
	v_mov_b32_e32 v97, v2
	v_mov_b32_e32 v106, v2
	v_mov_b32_e32 v107, v2
	v_mov_b32_e32 v108, v2
	v_mov_b32_e32 v109, v2
	v_mov_b32_e32 v110, v2
	v_mov_b32_e32 v111, v2
	v_mov_b32_e32 v112, v2
	v_mov_b32_e32 v113, v2
	v_mov_b32_e32 v122, v2
	v_mov_b32_e32 v123, v2
	v_mov_b32_e32 v124, v2
	v_mov_b32_e32 v125, v2
	v_mov_b32_e32 v126, v2
	v_mov_b32_e32 v127, v2
	v_mov_b32_e32 v128, v2
	v_mov_b32_e32 v129, v2
	v_readfirstlane_b32 s100, v0
	s_bitcmp0_b32 s100, 8
	s_cbranch_scc0 .Lfp6_prio_skip3
	s_setprio 1
